# diff attention LDS-DMA block: the eight s_nop fillers after the M0 writes replaced by the address adds and the second tile's K-fragment reads
# speedup vs baseline: 1.0014x; 1.0014x over previous
; template <bool HAS_QK, bool HAS_PV> ...
;     ...
;     if (HAS_QK) {
;         const float c0 = beta - mrun;
; #pragma unroll
;         for (int r = 0; r < 16; ++r) { s0[r] = c0; s1[r] = c0; }
; #pragma unroll
;         for (int s4 = 0; s4 < 4; ++s4) {
;             const bf16x8 a0 = KFRAG(Kt, kb0, kb1, 0, 0, s4), a1 = KFRAG(Kt, kb0, kb1, 1, 0, s4);
;             s0 = __builtin_amdgcn_mfma_f32_32x32x16_bf16(a0, qf[s4], s0, 0, 0, 0);
;             s1 = __builtin_amdgcn_mfma_f32_32x32x16_bf16(a1, qf[s4], s1, 0, 0, 0);
;         }
.Lcreg_ok_a:
	s_andn2_b64 vcc, exec, s[4:5]
	v_mfma_f32_32x32x16_bf16 v[128:143], v[220:223], v[144:147], v[194:209]
	ds_read_b128 v[220:223], v248 offset:512
	v_mfma_f32_32x32x16_bf16 v[80:95], v[224:227], v[144:147], v[194:209]
	ds_read_b128 v[224:227], v248 offset:8704
	v_mfma_f32_32x32x16_bf16 v[128:143], v[228:231], v[148:151], v[128:143]
	ds_read_b128 v[228:231], v249 offset:512
	v_mfma_f32_32x32x16_bf16 v[80:95], v[232:235], v[148:151], v[80:95]
	ds_read_b128 v[232:235], v249 offset:8704
	s_waitcnt lgkmcnt(3)
	v_mfma_f32_32x32x16_bf16 v[128:143], v[220:223], v[152:155], v[128:143]
	s_waitcnt lgkmcnt(2)
	v_mfma_f32_32x32x16_bf16 v[80:95], v[224:227], v[152:155], v[80:95]
	s_waitcnt lgkmcnt(1)
	v_mfma_f32_32x32x16_bf16 v[128:143], v[228:231], v[156:159], v[128:143]
	s_waitcnt lgkmcnt(0)
	v_mfma_f32_32x32x16_bf16 v[80:95], v[232:235], v[156:159], v[80:95]
	s_cmp_ge_u32 s35, s17
	s_cbranch_scc1 .Ldiff_nodma
	s_and_b32 s4, s34, 0x10000
	s_add_i32 s4, s24, s4
	v_readlane_b32 s10, v247, 0
	v_readlane_b32 s11, v247, 1
	s_add_i32 s56, s29, 0x80
	s_lshl_b32 s56, s56, 10
	s_add_u32 s10, s10, s56
	s_addc_u32 s11, s11, 0
	s_mov_b32 m0, s4
	s_add_u32 s56, s10, s72
	s_addc_u32 s57, s11, s73
	global_load_lds_dwordx4 v250, s[56:57]
	s_add_i32 m0, s4, 0x2000
	ds_read_b128 v[220:223], v248 offset:32768
	global_load_lds_dwordx4 v251, s[56:57]
	s_add_i32 m0, s4, 0x4000
	s_add_u32 s56, s10, s74
	s_addc_u32 s57, s11, s75
	global_load_lds_dwordx4 v250, s[56:57]
	s_add_i32 m0, s4, 0x6000
	ds_read_b128 v[224:227], v249 offset:32768
	global_load_lds_dwordx4 v251, s[56:57]
	s_add_i32 m0, s4, 0x8000
	s_add_u32 s56, s10, s68
	s_addc_u32 s57, s11, s69
	global_load_lds_dwordx4 v250, s[56:57]
	s_add_i32 m0, s4, 0xa000
	ds_read_b128 v[228:231], v248 offset:33280
	global_load_lds_dwordx4 v251, s[56:57]
	s_add_i32 m0, s4, 0xc000
	s_add_u32 s56, s10, s96
	s_addc_u32 s57, s11, s97
	global_load_lds_dwordx4 v250, s[56:57]
	s_add_i32 m0, s4, 0xe000
	ds_read_b128 v[232:235], v249 offset:33280
	global_load_lds_dwordx4 v251, s[56:57]
	s_branch .Ldiff_dma_done
.Ldiff_nodma:
	ds_read_b128 v[220:223], v248 offset:32768
	ds_read_b128 v[224:227], v249 offset:32768
	ds_read_b128 v[228:231], v248 offset:33280
	ds_read_b128 v[232:235], v249 offset:33280
	s_nop 10
